# MLA loop: one lgkmcnt wait per three MFMAs
# speedup vs baseline: 1.0467x; 1.0012x over previous
.LBB0_859:
	ds_read_b128 v[236:239], v214 offset:8192
	ds_read_b128 v[240:243], v215 offset:8192
	ds_read_b128 v[244:247], v216 offset:8192
	ds_read_b128 v[248:251], v217 offset:8192
	ds_read_b128 v[252:255], v218 offset:8192
	ds_read_b128 v[176:179], v219 offset:8192
	v_exp_f32_e32 v97, v97
	v_exp_f32_e32 v99, v99
	v_exp_f32_e32 v100, v100
	v_exp_f32_e32 v101, v101
	v_exp_f32_e32 v102, v102
	v_exp_f32_e32 v103, v103
	v_exp_f32_e32 v106, v106
	v_exp_f32_e32 v107, v107
	s_waitcnt lgkmcnt(3)
	v_mfma_f32_32x32x16_bf16 v[80:95], v[236:239], v[144:147], v[64:79]
	ds_read_b128 v[180:183], v220 offset:8192
	v_exp_f32_e32 v108, v108
	v_exp_f32_e32 v109, v109
	v_exp_f32_e32 v110, v110
	v_exp_f32_e32 v111, v111
	v_mfma_f32_32x32x16_bf16 v[80:95], v[240:243], v[156:159], v[80:95]
	ds_read_b128 v[236:239], v221 offset:8192
	s_add_u32 s98, s34, s60
	s_addc_u32 s99, s35, s59
	s_add_u32 s98, s98, 0x140fc000
	s_addc_u32 s99, s99, 0
	s_add_u32 s100, s34, s62
	s_addc_u32 s101, s35, s61
	s_add_u32 s100, s100, 0x171b0100
	s_addc_u32 s101, s101, 0
	s_mov_b32 m0, s52
	s_cmp_lg_u64 s[24:25], 0
	s_cselect_b32 s4, s100, s98
	s_cselect_b32 s5, s101, s99
	global_load_lds_dwordx4 v190, s[4:5]
	s_mov_b32 m0, s53
	s_cmp_lg_u64 s[26:27], 0
	s_cselect_b32 s4, s100, s98
	s_cselect_b32 s5, s101, s99
	global_load_lds_dwordx4 v192, s[4:5]
	s_mov_b32 m0, s54
	s_cmp_lg_u64 s[28:29], 0
	s_cselect_b32 s4, s100, s98
	s_cselect_b32 s5, s101, s99
	global_load_lds_dwordx4 v194, s[4:5]
	s_mov_b32 m0, s55
	s_cmp_lg_u64 s[30:31], 0
	s_cselect_b32 s4, s100, s98
	s_cselect_b32 s5, s101, s99
	global_load_lds_dwordx4 v196, s[4:5]
	s_mov_b32 m0, s56
	s_cmp_lg_u64 s[6:7], 0
	s_cselect_b32 s4, s100, s98
	s_cselect_b32 s5, s101, s99
	global_load_lds_dwordx4 v198, s[4:5]
	v_mfma_f32_32x32x16_bf16 v[80:95], v[244:247], v[168:171], v[80:95]
	ds_read_b128 v[240:243], v205 offset:53248
	s_waitcnt lgkmcnt(3)
	v_mfma_f32_32x32x16_bf16 v[80:95], v[248:251], v[172:175], v[80:95]
	ds_read_b128 v[244:247], v207 offset:53248
	v_mfma_f32_32x32x16_bf16 v[80:95], v[252:255], v[164:167], v[80:95]
	ds_read_b128 v[248:251], v209 offset:53248
	v_mfma_f32_32x32x16_bf16 v[80:95], v[176:179], v[160:163], v[80:95]
	ds_read_b128 v[252:255], v211 offset:53248
	s_waitcnt lgkmcnt(3)
	v_mfma_f32_32x32x16_bf16 v[80:95], v[180:183], v[152:155], v[80:95]
	ds_read_b128 v[176:179], v225
	v_mfma_f32_32x32x16_bf16 v[80:95], v[236:239], v[148:151], v[80:95]
	ds_read_b128 v[180:183], v225 offset:4096
	v_mfma_f32_32x32x16_bf16 v[80:95], v[240:243], v[140:143], v[80:95]
	ds_read_b128 v[236:239], v225 offset:8192
	s_waitcnt lgkmcnt(3)
	v_mfma_f32_32x32x16_bf16 v[80:95], v[244:247], v[136:139], v[80:95]
	ds_read_b128 v[240:243], v225 offset:12288
	v_mfma_f32_32x32x16_bf16 v[80:95], v[248:251], v[132:135], v[80:95]
	ds_read_b128 v[244:247], v226
	v_mfma_f32_32x32x16_bf16 v[80:95], v[252:255], v[128:131], v[80:95]
	ds_read_b128 v[248:251], v226 offset:4096
	v_exp_f32_e32 v112, v96
	v_exp_f32_e32 v113, v98
	v_exp_f32_e32 v114, v104
	v_exp_f32_e32 v115, v105
	v_add_f32_e32 v96, 0, v112
	v_add_f32_e32 v96, v97, v96
	v_add_f32_e32 v96, v113, v96
	v_add_f32_e32 v96, v99, v96
	v_add_f32_e32 v96, v100, v96
	v_add_f32_e32 v96, v101, v96
	v_add_f32_e32 v96, v102, v96
	v_add_f32_e32 v96, v103, v96
	v_cvt_pk_bf16_f32 v100, v100, v101
	v_cvt_pk_bf16_f32 v101, v102, v103
	v_cvt_pk_bf16_f32 v98, v112, v97
	v_cvt_pk_bf16_f32 v99, v113, v99
	v_max_f32_e32 v97, v81, v81
	v_add_f32_e32 v96, v114, v96
	s_waitcnt lgkmcnt(3)
	v_mfma_f32_32x32x16_bf16 v[48:63], v[176:179], v[98:101], v[48:63]
	ds_read_b128 v[252:255], v226 offset:8192
	v_add_f32_e32 v96, v115, v96
	v_add_f32_e32 v96, v106, v96
	v_add_f32_e32 v96, v107, v96
	v_add_f32_e32 v96, v108, v96
	v_add_f32_e32 v96, v109, v96
	v_add_f32_e32 v96, v110, v96
	v_mfma_f32_32x32x16_bf16 v[32:47], v[180:183], v[98:101], v[32:47]
	ds_read_b128 v[176:179], v226 offset:12288
	v_add_f32_e32 v96, v111, v96
	v_add_f32_e32 v112, v230, v96
	v_mfma_f32_32x32x16_bf16 v[16:31], v[236:239], v[98:101], v[16:31]
	ds_read_b128 v[180:183], v214 offset:16384
	s_waitcnt lgkmcnt(3)
	v_mfma_f32_32x32x16_bf16 v[0:15], v[240:243], v[98:101], v[0:15]
	ds_read_b128 v[236:239], v215 offset:16384
	v_cvt_pk_bf16_f32 v98, v114, v115
	v_cvt_pk_bf16_f32 v99, v106, v107
	v_cvt_pk_bf16_f32 v100, v108, v109
	v_cvt_pk_bf16_f32 v101, v110, v111
	s_nop 0
	s_nop 0
	v_mfma_f32_32x32x16_bf16 v[48:63], v[244:247], v[98:101], v[48:63]
	ds_read_b128 v[240:243], v216 offset:16384
	v_mfma_f32_32x32x16_bf16 v[32:47], v[248:251], v[98:101], v[32:47]
	ds_read_b128 v[244:247], v217 offset:16384
	s_waitcnt lgkmcnt(3)
	v_mfma_f32_32x32x16_bf16 v[16:31], v[252:255], v[98:101], v[16:31]
	ds_read_b128 v[248:251], v218 offset:16384
	v_mfma_f32_32x32x16_bf16 v[0:15], v[176:179], v[98:101], v[0:15]
	ds_read_b128 v[252:255], v219 offset:16384
	v_max_f32_e32 v98, v80, v80
	v_max_f32_e32 v97, v98, v97
	v_max3_f32 v97, v97, v82, v83
	v_max3_f32 v97, v97, v84, v85
	v_max3_f32 v97, v97, v86, v87
	v_max3_f32 v97, v97, v88, v89
	v_max3_f32 v97, v97, v90, v91
	v_max3_f32 v97, v97, v92, v93
	v_max3_f32 v97, v97, v94, v95
	ds_bpermute_b32 v98, v229, v97
	s_waitcnt lgkmcnt(0)
	v_max_f32_e32 v96, v98, v98
	v_max_f32_e32 v96, v97, v96
	v_cmp_lt_f32_e32 vcc, 0, v96
	s_cbranch_vccz .LBB0_861
	v_max_f32_e32 v96, v96, v96
	v_max_f32_e32 v96, 0, v96
	v_exp_f32_e64 v98, -v96
	v_pk_add_f32 v[80:81], v[80:81], v[96:97] op_sel_hi:[1,0] neg_lo:[0,1] neg_hi:[0,1]
	v_pk_add_f32 v[82:83], v[82:83], v[96:97] op_sel_hi:[1,0] neg_lo:[0,1] neg_hi:[0,1]
	v_pk_add_f32 v[84:85], v[84:85], v[96:97] op_sel_hi:[1,0] neg_lo:[0,1] neg_hi:[0,1]
	v_mul_f32_e32 v112, v112, v98
	v_pk_add_f32 v[86:87], v[86:87], v[96:97] op_sel_hi:[1,0] neg_lo:[0,1] neg_hi:[0,1]
	v_pk_add_f32 v[88:89], v[88:89], v[96:97] op_sel_hi:[1,0] neg_lo:[0,1] neg_hi:[0,1]
	v_pk_add_f32 v[90:91], v[90:91], v[96:97] op_sel_hi:[1,0] neg_lo:[0,1] neg_hi:[0,1]
	v_pk_add_f32 v[92:93], v[92:93], v[96:97] op_sel_hi:[1,0] neg_lo:[0,1] neg_hi:[0,1]
	v_sub_f32_e32 v79, v79, v96
	v_sub_f32_e32 v78, v78, v96
	v_sub_f32_e32 v77, v77, v96
	v_sub_f32_e32 v76, v76, v96
	v_sub_f32_e32 v75, v75, v96
	v_sub_f32_e32 v74, v74, v96
	v_sub_f32_e32 v73, v73, v96
	v_sub_f32_e32 v72, v72, v96
	v_sub_f32_e32 v71, v71, v96
	v_sub_f32_e32 v70, v70, v96
	v_sub_f32_e32 v69, v69, v96
	v_sub_f32_e32 v68, v68, v96
	v_sub_f32_e32 v67, v67, v96
	v_sub_f32_e32 v66, v66, v96
	v_sub_f32_e32 v65, v65, v96
	v_sub_f32_e32 v64, v64, v96
	v_pk_add_f32 v[94:95], v[94:95], v[96:97] op_sel_hi:[1,0] neg_lo:[0,1] neg_hi:[0,1]
	v_pk_mul_f32 v[62:63], v[62:63], v[98:99] op_sel_hi:[1,0]
	v_pk_mul_f32 v[60:61], v[60:61], v[98:99] op_sel_hi:[1,0]
	v_pk_mul_f32 v[58:59], v[58:59], v[98:99] op_sel_hi:[1,0]
	v_pk_mul_f32 v[56:57], v[56:57], v[98:99] op_sel_hi:[1,0]
	v_pk_mul_f32 v[54:55], v[54:55], v[98:99] op_sel_hi:[1,0]
	v_pk_mul_f32 v[52:53], v[52:53], v[98:99] op_sel_hi:[1,0]
	v_pk_mul_f32 v[50:51], v[50:51], v[98:99] op_sel_hi:[1,0]
	v_pk_mul_f32 v[48:49], v[48:49], v[98:99] op_sel_hi:[1,0]
	v_pk_mul_f32 v[46:47], v[46:47], v[98:99] op_sel_hi:[1,0]
	v_pk_mul_f32 v[44:45], v[44:45], v[98:99] op_sel_hi:[1,0]
	v_pk_mul_f32 v[42:43], v[42:43], v[98:99] op_sel_hi:[1,0]
	v_pk_mul_f32 v[40:41], v[40:41], v[98:99] op_sel_hi:[1,0]
	v_pk_mul_f32 v[38:39], v[38:39], v[98:99] op_sel_hi:[1,0]
	v_pk_mul_f32 v[36:37], v[36:37], v[98:99] op_sel_hi:[1,0]
	v_pk_mul_f32 v[34:35], v[34:35], v[98:99] op_sel_hi:[1,0]
	v_pk_mul_f32 v[32:33], v[32:33], v[98:99] op_sel_hi:[1,0]
	v_pk_mul_f32 v[30:31], v[30:31], v[98:99] op_sel_hi:[1,0]
	v_pk_mul_f32 v[28:29], v[28:29], v[98:99] op_sel_hi:[1,0]
	v_pk_mul_f32 v[26:27], v[26:27], v[98:99] op_sel_hi:[1,0]
	v_pk_mul_f32 v[24:25], v[24:25], v[98:99] op_sel_hi:[1,0]
	v_pk_mul_f32 v[22:23], v[22:23], v[98:99] op_sel_hi:[1,0]
	v_pk_mul_f32 v[20:21], v[20:21], v[98:99] op_sel_hi:[1,0]
	v_pk_mul_f32 v[18:19], v[18:19], v[98:99] op_sel_hi:[1,0]
	v_pk_mul_f32 v[16:17], v[16:17], v[98:99] op_sel_hi:[1,0]
	v_pk_mul_f32 v[14:15], v[14:15], v[98:99] op_sel_hi:[1,0]
	v_pk_mul_f32 v[12:13], v[12:13], v[98:99] op_sel_hi:[1,0]
	v_pk_mul_f32 v[10:11], v[10:11], v[98:99] op_sel_hi:[1,0]
	v_pk_mul_f32 v[8:9], v[8:9], v[98:99] op_sel_hi:[1,0]
	v_pk_mul_f32 v[6:7], v[6:7], v[98:99] op_sel_hi:[1,0]
	v_pk_mul_f32 v[4:5], v[4:5], v[98:99] op_sel_hi:[1,0]
	v_pk_mul_f32 v[2:3], v[2:3], v[98:99] op_sel_hi:[1,0]
	v_pk_mul_f32 v[0:1], v[0:1], v[98:99] op_sel_hi:[1,0]
.LBB0_861:
	v_exp_f32_e32 v113, v80
	v_exp_f32_e32 v122, v81
	v_exp_f32_e32 v123, v82
	v_mfma_f32_32x32x16_bf16 v[96:111], v[180:183], v[144:147], v[64:79]
	ds_read_b128 v[176:179], v220 offset:16384
	v_exp_f32_e32 v124, v83
	v_exp_f32_e32 v125, v84
	v_exp_f32_e32 v126, v85
	v_exp_f32_e32 v127, v86
	v_exp_f32_e32 v230, v87
	v_exp_f32_e32 v88, v88
	v_exp_f32_e32 v89, v89
	v_mfma_f32_32x32x16_bf16 v[96:111], v[236:239], v[156:159], v[96:111]
	ds_read_b128 v[180:183], v221 offset:16384
	v_exp_f32_e32 v90, v90
	v_exp_f32_e32 v91, v91
	v_exp_f32_e32 v92, v92
	v_exp_f32_e32 v93, v93
	v_exp_f32_e32 v94, v94
	v_exp_f32_e32 v95, v95
	v_mfma_f32_32x32x16_bf16 v[96:111], v[240:243], v[168:171], v[96:111]
	ds_read_b128 v[236:239], v205 offset:57344
	v_mfma_f32_32x32x16_bf16 v[96:111], v[244:247], v[172:175], v[96:111]
	ds_read_b128 v[240:243], v207 offset:57344
	v_mfma_f32_32x32x16_bf16 v[96:111], v[248:251], v[164:167], v[96:111]
	ds_read_b128 v[244:247], v209 offset:57344
	v_mfma_f32_32x32x16_bf16 v[96:111], v[252:255], v[160:163], v[96:111]
	ds_read_b128 v[248:251], v211 offset:57344
	s_waitcnt lgkmcnt(3)
	v_mfma_f32_32x32x16_bf16 v[96:111], v[176:179], v[152:155], v[96:111]
	ds_read_b128 v[252:255], v227
	v_mfma_f32_32x32x16_bf16 v[96:111], v[180:183], v[148:151], v[96:111]
	ds_read_b128 v[176:179], v227 offset:4096
	v_mfma_f32_32x32x16_bf16 v[96:111], v[236:239], v[140:143], v[96:111]
	ds_read_b128 v[180:183], v227 offset:8192
	s_waitcnt lgkmcnt(3)
	v_mfma_f32_32x32x16_bf16 v[96:111], v[240:243], v[136:139], v[96:111]
	ds_read_b128 v[236:239], v227 offset:12288
	v_mfma_f32_32x32x16_bf16 v[96:111], v[244:247], v[132:135], v[96:111]
	ds_read_b128 v[240:243], v228 offset:4096
	v_cvt_pk_bf16_f32 v114, v113, v122
	v_cvt_pk_bf16_f32 v115, v123, v124
	v_cvt_pk_bf16_f32 v116, v125, v126
	v_cvt_pk_bf16_f32 v117, v127, v230
	v_mfma_f32_32x32x16_bf16 v[96:111], v[248:251], v[128:131], v[96:111]
	ds_read_b128 v[244:247], v228
	v_add_f32_e32 v118, 0, v113
	v_add_f32_e32 v113, v122, v118
	v_add_f32_e32 v113, v123, v113
	s_waitcnt lgkmcnt(3)
	v_mfma_f32_32x32x16_bf16 v[48:63], v[252:255], v[114:117], v[48:63]
	ds_read_b128 v[248:251], v228 offset:8192
	v_add_f32_e32 v80, v124, v113
	v_add_f32_e32 v80, v125, v80
	v_add_f32_e32 v80, v126, v80
	v_add_f32_e32 v113, v127, v80
	v_mfma_f32_32x32x16_bf16 v[32:47], v[176:179], v[114:117], v[32:47]
	ds_read_b128 v[252:255], v228 offset:12288
	v_add_f32_e32 v84, v230, v113
	v_add_f32_e32 v84, v88, v84
	v_add_f32_e32 v113, v89, v84
	v_mfma_f32_32x32x16_bf16 v[16:31], v[180:183], v[114:117], v[16:31]
	ds_read_b128 v[176:179], v214 offset:24576
	v_add_f32_e32 v80, v90, v113
	v_add_f32_e32 v80, v91, v80
	v_add_f32_e32 v80, v92, v80
	v_add_f32_e32 v113, v93, v80
	v_add_f32_e32 v113, v94, v113
	s_waitcnt lgkmcnt(3)
	v_mfma_f32_32x32x16_bf16 v[0:15], v[236:239], v[114:117], v[0:15]
	ds_read_b128 v[180:183], v215 offset:24576
	v_cvt_pk_bf16_f32 v84, v88, v89
	v_cvt_pk_bf16_f32 v85, v90, v91
	v_cvt_pk_bf16_f32 v86, v92, v93
	v_max_f32_e32 v92, v97, v97
	v_max_f32_e32 v93, v96, v96
	v_max_f32_e32 v92, v93, v92
	v_max3_f32 v92, v92, v98, v99
	v_max3_f32 v92, v92, v100, v101
	v_cvt_pk_bf16_f32 v87, v94, v95
	v_max3_f32 v92, v92, v102, v103
	v_add_f32_e32 v94, v95, v113
	v_mfma_f32_32x32x16_bf16 v[32:47], v[240:243], v[84:87], v[32:47]
	ds_read_b128 v[236:239], v216 offset:24576
	v_max3_f32 v88, v92, v104, v105
	v_max3_f32 v88, v88, v106, v107
	v_max3_f32 v88, v88, v108, v109
	v_max3_f32 v92, v88, v110, v111
	ds_bpermute_b32 v93, v229, v92
	v_add_f32_e32 v112, v112, v94
	v_mfma_f32_32x32x16_bf16 v[48:63], v[244:247], v[84:87], v[48:63]
	ds_read_b128 v[240:243], v217 offset:24576
	s_waitcnt vmcnt(0)
	s_barrier
	s_waitcnt lgkmcnt(4)
	v_mfma_f32_32x32x16_bf16 v[16:31], v[248:251], v[84:87], v[16:31]
	ds_read_b128 v[244:247], v218 offset:24576
	s_waitcnt lgkmcnt(2)
	v_max_f32_e32 v80, v93, v93
	v_max_f32_e32 v80, v92, v80
	v_cmp_lt_f32_e32 vcc, 0, v80
	v_mfma_f32_32x32x16_bf16 v[0:15], v[252:255], v[84:87], v[0:15]
	ds_read_b128 v[248:251], v219 offset:24576
	s_cbranch_vccz .LBB0_863
	v_max_f32_e32 v80, v80, v80
	v_max_f32_e32 v80, 0, v80
	v_exp_f32_e64 v82, -v80
	v_pk_add_f32 v[96:97], v[96:97], v[80:81] op_sel_hi:[1,0] neg_lo:[0,1] neg_hi:[0,1]
	v_pk_add_f32 v[98:99], v[98:99], v[80:81] op_sel_hi:[1,0] neg_lo:[0,1] neg_hi:[0,1]
	v_pk_add_f32 v[100:101], v[100:101], v[80:81] op_sel_hi:[1,0] neg_lo:[0,1] neg_hi:[0,1]
	v_mul_f32_e32 v112, v112, v82
	v_pk_add_f32 v[102:103], v[102:103], v[80:81] op_sel_hi:[1,0] neg_lo:[0,1] neg_hi:[0,1]
	v_pk_add_f32 v[104:105], v[104:105], v[80:81] op_sel_hi:[1,0] neg_lo:[0,1] neg_hi:[0,1]
	v_pk_add_f32 v[106:107], v[106:107], v[80:81] op_sel_hi:[1,0] neg_lo:[0,1] neg_hi:[0,1]
	v_pk_add_f32 v[108:109], v[108:109], v[80:81] op_sel_hi:[1,0] neg_lo:[0,1] neg_hi:[0,1]
	v_sub_f32_e32 v79, v79, v80
	v_sub_f32_e32 v78, v78, v80
	v_sub_f32_e32 v77, v77, v80
	v_sub_f32_e32 v76, v76, v80
	v_sub_f32_e32 v75, v75, v80
	v_sub_f32_e32 v74, v74, v80
	v_sub_f32_e32 v73, v73, v80
	v_sub_f32_e32 v72, v72, v80
	v_sub_f32_e32 v71, v71, v80
	v_sub_f32_e32 v70, v70, v80
	v_sub_f32_e32 v69, v69, v80
	v_sub_f32_e32 v68, v68, v80
	v_sub_f32_e32 v67, v67, v80
	v_sub_f32_e32 v66, v66, v80
	v_sub_f32_e32 v65, v65, v80
	v_sub_f32_e32 v64, v64, v80
	v_pk_add_f32 v[110:111], v[110:111], v[80:81] op_sel_hi:[1,0] neg_lo:[0,1] neg_hi:[0,1]
	v_pk_mul_f32 v[62:63], v[62:63], v[82:83] op_sel_hi:[1,0]
	v_pk_mul_f32 v[60:61], v[60:61], v[82:83] op_sel_hi:[1,0]
	v_pk_mul_f32 v[58:59], v[58:59], v[82:83] op_sel_hi:[1,0]
	v_pk_mul_f32 v[56:57], v[56:57], v[82:83] op_sel_hi:[1,0]
	v_pk_mul_f32 v[54:55], v[54:55], v[82:83] op_sel_hi:[1,0]
	v_pk_mul_f32 v[52:53], v[52:53], v[82:83] op_sel_hi:[1,0]
	v_pk_mul_f32 v[50:51], v[50:51], v[82:83] op_sel_hi:[1,0]
	v_pk_mul_f32 v[48:49], v[48:49], v[82:83] op_sel_hi:[1,0]
	v_pk_mul_f32 v[46:47], v[46:47], v[82:83] op_sel_hi:[1,0]
	v_pk_mul_f32 v[44:45], v[44:45], v[82:83] op_sel_hi:[1,0]
	v_pk_mul_f32 v[42:43], v[42:43], v[82:83] op_sel_hi:[1,0]
	v_pk_mul_f32 v[40:41], v[40:41], v[82:83] op_sel_hi:[1,0]
	v_pk_mul_f32 v[38:39], v[38:39], v[82:83] op_sel_hi:[1,0]
	v_pk_mul_f32 v[36:37], v[36:37], v[82:83] op_sel_hi:[1,0]
	v_pk_mul_f32 v[34:35], v[34:35], v[82:83] op_sel_hi:[1,0]
	v_pk_mul_f32 v[32:33], v[32:33], v[82:83] op_sel_hi:[1,0]
	v_pk_mul_f32 v[30:31], v[30:31], v[82:83] op_sel_hi:[1,0]
	v_pk_mul_f32 v[28:29], v[28:29], v[82:83] op_sel_hi:[1,0]
	v_pk_mul_f32 v[26:27], v[26:27], v[82:83] op_sel_hi:[1,0]
	v_pk_mul_f32 v[24:25], v[24:25], v[82:83] op_sel_hi:[1,0]
	v_pk_mul_f32 v[22:23], v[22:23], v[82:83] op_sel_hi:[1,0]
	v_pk_mul_f32 v[20:21], v[20:21], v[82:83] op_sel_hi:[1,0]
	v_pk_mul_f32 v[18:19], v[18:19], v[82:83] op_sel_hi:[1,0]
	v_pk_mul_f32 v[16:17], v[16:17], v[82:83] op_sel_hi:[1,0]
	v_pk_mul_f32 v[14:15], v[14:15], v[82:83] op_sel_hi:[1,0]
	v_pk_mul_f32 v[12:13], v[12:13], v[82:83] op_sel_hi:[1,0]
	v_pk_mul_f32 v[10:11], v[10:11], v[82:83] op_sel_hi:[1,0]
	v_pk_mul_f32 v[8:9], v[8:9], v[82:83] op_sel_hi:[1,0]
	v_pk_mul_f32 v[6:7], v[6:7], v[82:83] op_sel_hi:[1,0]
	v_pk_mul_f32 v[4:5], v[4:5], v[82:83] op_sel_hi:[1,0]
	v_pk_mul_f32 v[2:3], v[2:3], v[82:83] op_sel_hi:[1,0]
	v_pk_mul_f32 v[0:1], v[0:1], v[82:83] op_sel_hi:[1,0]

.Lmla_dma_skip_t1:
	v_cvt_pk_bf16_f32 v124, v100, v101
	v_cvt_pk_bf16_f32 v125, v102, v103
	v_exp_f32_e32 v104, v104
	v_exp_f32_e32 v105, v105
	v_exp_f32_e32 v106, v106
	v_exp_f32_e32 v107, v107
	v_mfma_f32_32x32x16_bf16 v[80:95], v[236:239], v[168:171], v[80:95]
	ds_read_b128 v[180:183], v205 offset:61440
	v_exp_f32_e32 v108, v108
	v_exp_f32_e32 v109, v109
	v_exp_f32_e32 v110, v110
	v_exp_f32_e32 v111, v111
	s_add_i32 s16, s8, 3
	s_cmp_lt_u32 s16, s9
	s_cselect_b64 s[10:11], -1, 0
	s_waitcnt lgkmcnt(3)
	v_mfma_f32_32x32x16_bf16 v[80:95], v[240:243], v[172:175], v[80:95]
	ds_read_b128 v[236:239], v207 offset:61440
	s_cmp_ge_u32 s16, s9
	v_mfma_f32_32x32x16_bf16 v[80:95], v[244:247], v[164:167], v[80:95]
	ds_read_b128 v[240:243], v209 offset:61440
	v_mfma_f32_32x32x16_bf16 v[80:95], v[248:251], v[160:163], v[80:95]
	ds_read_b128 v[244:247], v211 offset:61440
	s_waitcnt lgkmcnt(3)
	v_mfma_f32_32x32x16_bf16 v[80:95], v[252:255], v[152:155], v[80:95]
	ds_read_b128 v[248:251], v225 offset:16384
	v_mfma_f32_32x32x16_bf16 v[80:95], v[176:179], v[148:151], v[80:95]
	ds_read_b128 v[252:255], v225 offset:20480
	v_mfma_f32_32x32x16_bf16 v[80:95], v[180:183], v[140:143], v[80:95]
	ds_read_b128 v[176:179], v225 offset:24576
	s_waitcnt lgkmcnt(3)
	v_mfma_f32_32x32x16_bf16 v[80:95], v[236:239], v[136:139], v[80:95]
	ds_read_b128 v[180:183], v225 offset:28672
	v_mfma_f32_32x32x16_bf16 v[80:95], v[240:243], v[132:135], v[80:95]
	ds_read_b128 v[236:239], v226 offset:16384
	v_mfma_f32_32x32x16_bf16 v[80:95], v[244:247], v[128:131], v[80:95]
	ds_read_b128 v[240:243], v226 offset:20480
	s_waitcnt lgkmcnt(3)
	v_mfma_f32_32x32x16_bf16 v[48:63], v[248:251], v[122:125], v[48:63]
	ds_read_b128 v[244:247], v226 offset:24576
	s_nop 8
	v_max_f32_e32 v113, v81, v81
	v_max_f32_e32 v126, v80, v80
	v_max_f32_e32 v113, v126, v113
	v_max3_f32 v113, v113, v82, v83
	v_max3_f32 v113, v113, v84, v85
	v_max3_f32 v113, v113, v86, v87
	v_max3_f32 v113, v113, v88, v89
	v_mfma_f32_32x32x16_bf16 v[32:47], v[252:255], v[122:125], v[32:47]
	ds_read_b128 v[248:251], v226 offset:28672
	v_max3_f32 v113, v113, v90, v91
	v_max3_f32 v113, v113, v92, v93
	v_max3_f32 v113, v113, v94, v95
	v_mfma_f32_32x32x16_bf16 v[16:31], v[176:179], v[122:125], v[16:31]
	ds_read_b128 v[252:255], v214 offset:32768
	s_waitcnt lgkmcnt(3)
	v_mfma_f32_32x32x16_bf16 v[0:15], v[180:183], v[122:125], v[0:15]
	ds_read_b128 v[176:179], v215 offset:32768
	v_cvt_pk_bf16_f32 v118, v104, v105
	v_cvt_pk_bf16_f32 v119, v106, v107
	v_cvt_pk_bf16_f32 v120, v108, v109
	v_cvt_pk_bf16_f32 v121, v110, v111
	s_nop 0
	s_nop 0
	v_mfma_f32_32x32x16_bf16 v[48:63], v[236:239], v[118:121], v[48:63]
	ds_read_b128 v[180:183], v216 offset:32768
	v_mfma_f32_32x32x16_bf16 v[32:47], v[240:243], v[118:121], v[32:47]
	ds_read_b128 v[236:239], v217 offset:32768
	s_waitcnt lgkmcnt(3)
	v_mfma_f32_32x32x16_bf16 v[16:31], v[244:247], v[118:121], v[16:31]
	ds_read_b128 v[240:243], v218 offset:32768
	ds_bpermute_b32 v114, v229, v113
	v_mfma_f32_32x32x16_bf16 v[0:15], v[248:251], v[118:121], v[0:15]
	ds_read_b128 v[244:247], v219 offset:32768

.LBB0_867:
	v_exp_f32_e32 v113, v80
	v_exp_f32_e32 v122, v81
	v_exp_f32_e32 v123, v82
	v_mfma_f32_32x32x16_bf16 v[96:111], v[252:255], v[144:147], v[64:79]
	ds_read_b128 v[248:251], v220 offset:32768
	v_exp_f32_e32 v124, v83
	v_exp_f32_e32 v125, v84
	v_exp_f32_e32 v126, v85
	v_exp_f32_e32 v127, v86
	v_exp_f32_e32 v230, v87
	v_exp_f32_e32 v88, v88
	v_exp_f32_e32 v89, v89
	v_mfma_f32_32x32x16_bf16 v[96:111], v[176:179], v[156:159], v[96:111]
	ds_read_b128 v[252:255], v221 offset:32768
	v_exp_f32_e32 v90, v90
	v_exp_f32_e32 v91, v91
	v_exp_f32_e32 v92, v92
	v_exp_f32_e32 v93, v93
	v_exp_f32_e32 v94, v94
	v_exp_f32_e32 v95, v95
	v_mfma_f32_32x32x16_bf16 v[96:111], v[180:183], v[168:171], v[96:111]
	ds_read_b128 v[176:179], v206 offset:16384
	v_mfma_f32_32x32x16_bf16 v[96:111], v[236:239], v[172:175], v[96:111]
	ds_read_b128 v[180:183], v208 offset:16384
	v_mfma_f32_32x32x16_bf16 v[96:111], v[240:243], v[164:167], v[96:111]
	ds_read_b128 v[236:239], v210 offset:16384
	s_waitcnt lgkmcnt(3)
	v_mfma_f32_32x32x16_bf16 v[96:111], v[244:247], v[160:163], v[96:111]
	ds_read_b128 v[240:243], v212 offset:16384
	v_mfma_f32_32x32x16_bf16 v[96:111], v[248:251], v[152:155], v[96:111]
	ds_read_b128 v[244:247], v227 offset:16384
	v_mfma_f32_32x32x16_bf16 v[96:111], v[252:255], v[148:151], v[96:111]
	ds_read_b128 v[248:251], v227 offset:20480
	s_waitcnt lgkmcnt(3)
	v_mfma_f32_32x32x16_bf16 v[96:111], v[176:179], v[140:143], v[96:111]
	ds_read_b128 v[252:255], v227 offset:24576
	v_mfma_f32_32x32x16_bf16 v[96:111], v[180:183], v[136:139], v[96:111]
	ds_read_b128 v[176:179], v227 offset:28672
	v_mfma_f32_32x32x16_bf16 v[96:111], v[236:239], v[132:135], v[96:111]
	ds_read_b128 v[180:183], v228 offset:20480
	v_cvt_pk_bf16_f32 v114, v113, v122
	v_cvt_pk_bf16_f32 v115, v123, v124
	v_cvt_pk_bf16_f32 v116, v125, v126
	v_cvt_pk_bf16_f32 v117, v127, v230
	s_waitcnt lgkmcnt(3)
	v_mfma_f32_32x32x16_bf16 v[96:111], v[240:243], v[128:131], v[96:111]
	ds_read_b128 v[236:239], v228 offset:16384
	v_add_f32_e32 v118, 0, v113
	v_add_f32_e32 v113, v122, v118
	v_add_f32_e32 v113, v123, v113
	v_mfma_f32_32x32x16_bf16 v[48:63], v[244:247], v[114:117], v[48:63]
	ds_read_b128 v[240:243], v228 offset:24576
	v_add_f32_e32 v80, v124, v113
	v_add_f32_e32 v80, v125, v80
	v_add_f32_e32 v80, v126, v80
	v_add_f32_e32 v113, v127, v80
	v_mfma_f32_32x32x16_bf16 v[32:47], v[248:251], v[114:117], v[32:47]
	ds_read_b128 v[244:247], v228 offset:28672
	v_add_f32_e32 v84, v230, v113
	v_add_f32_e32 v84, v88, v84
	v_add_f32_e32 v113, v89, v84
	s_waitcnt lgkmcnt(3)
	v_mfma_f32_32x32x16_bf16 v[16:31], v[252:255], v[114:117], v[16:31]
	ds_read_b128 v[248:251], v214 offset:40960
	v_add_f32_e32 v80, v90, v113
	v_add_f32_e32 v80, v91, v80
	v_add_f32_e32 v80, v92, v80
	v_add_f32_e32 v113, v93, v80
	v_add_f32_e32 v113, v94, v113
	v_mfma_f32_32x32x16_bf16 v[0:15], v[176:179], v[114:117], v[0:15]
	ds_read_b128 v[252:255], v215 offset:40960
	v_cvt_pk_bf16_f32 v84, v88, v89
	v_cvt_pk_bf16_f32 v85, v90, v91
	v_cvt_pk_bf16_f32 v86, v92, v93
	v_max_f32_e32 v92, v97, v97
	v_max_f32_e32 v93, v96, v96
	v_max_f32_e32 v92, v93, v92
	v_max3_f32 v92, v92, v98, v99
	v_max3_f32 v92, v92, v100, v101
	v_cvt_pk_bf16_f32 v87, v94, v95
	v_max3_f32 v92, v92, v102, v103
	v_add_f32_e32 v94, v95, v113
	v_mfma_f32_32x32x16_bf16 v[32:47], v[180:183], v[84:87], v[32:47]
	ds_read_b128 v[176:179], v216 offset:40960
	v_max3_f32 v88, v92, v104, v105
	v_max3_f32 v88, v88, v106, v107
	v_max3_f32 v88, v88, v108, v109
	v_max3_f32 v92, v88, v110, v111
	ds_bpermute_b32 v93, v229, v92
	v_add_f32_e32 v112, v112, v94
	s_waitcnt lgkmcnt(4)
	v_mfma_f32_32x32x16_bf16 v[48:63], v[236:239], v[84:87], v[48:63]
	ds_read_b128 v[180:183], v217 offset:40960
	s_waitcnt vmcnt(0)
	s_barrier
	v_mfma_f32_32x32x16_bf16 v[16:31], v[240:243], v[84:87], v[16:31]
	ds_read_b128 v[236:239], v218 offset:40960
	s_waitcnt lgkmcnt(2)
	v_max_f32_e32 v80, v93, v93
	v_max_f32_e32 v80, v92, v80
	v_cmp_lt_f32_e32 vcc, 0, v80
	v_mfma_f32_32x32x16_bf16 v[0:15], v[244:247], v[84:87], v[0:15]
	ds_read_b128 v[240:243], v219 offset:40960
	s_cbranch_vccz .LBB0_869
	v_max_f32_e32 v80, v80, v80
	v_max_f32_e32 v80, 0, v80
	v_exp_f32_e64 v82, -v80
	v_pk_add_f32 v[96:97], v[96:97], v[80:81] op_sel_hi:[1,0] neg_lo:[0,1] neg_hi:[0,1]
	v_pk_add_f32 v[98:99], v[98:99], v[80:81] op_sel_hi:[1,0] neg_lo:[0,1] neg_hi:[0,1]
	v_pk_add_f32 v[100:101], v[100:101], v[80:81] op_sel_hi:[1,0] neg_lo:[0,1] neg_hi:[0,1]
	v_mul_f32_e32 v112, v112, v82
	v_pk_add_f32 v[102:103], v[102:103], v[80:81] op_sel_hi:[1,0] neg_lo:[0,1] neg_hi:[0,1]
	v_pk_add_f32 v[104:105], v[104:105], v[80:81] op_sel_hi:[1,0] neg_lo:[0,1] neg_hi:[0,1]
	v_pk_add_f32 v[106:107], v[106:107], v[80:81] op_sel_hi:[1,0] neg_lo:[0,1] neg_hi:[0,1]
	v_pk_add_f32 v[108:109], v[108:109], v[80:81] op_sel_hi:[1,0] neg_lo:[0,1] neg_hi:[0,1]
	v_sub_f32_e32 v79, v79, v80
	v_sub_f32_e32 v78, v78, v80
	v_sub_f32_e32 v77, v77, v80
	v_sub_f32_e32 v76, v76, v80
	v_sub_f32_e32 v75, v75, v80
	v_sub_f32_e32 v74, v74, v80
	v_sub_f32_e32 v73, v73, v80
	v_sub_f32_e32 v72, v72, v80
	v_sub_f32_e32 v71, v71, v80
	v_sub_f32_e32 v70, v70, v80
	v_sub_f32_e32 v69, v69, v80
	v_sub_f32_e32 v68, v68, v80
	v_sub_f32_e32 v67, v67, v80
	v_sub_f32_e32 v66, v66, v80
	v_sub_f32_e32 v65, v65, v80
	v_sub_f32_e32 v64, v64, v80
	v_pk_add_f32 v[110:111], v[110:111], v[80:81] op_sel_hi:[1,0] neg_lo:[0,1] neg_hi:[0,1]
	v_pk_mul_f32 v[62:63], v[62:63], v[82:83] op_sel_hi:[1,0]
	v_pk_mul_f32 v[60:61], v[60:61], v[82:83] op_sel_hi:[1,0]
	v_pk_mul_f32 v[58:59], v[58:59], v[82:83] op_sel_hi:[1,0]
	v_pk_mul_f32 v[56:57], v[56:57], v[82:83] op_sel_hi:[1,0]
	v_pk_mul_f32 v[54:55], v[54:55], v[82:83] op_sel_hi:[1,0]
	v_pk_mul_f32 v[52:53], v[52:53], v[82:83] op_sel_hi:[1,0]
	v_pk_mul_f32 v[50:51], v[50:51], v[82:83] op_sel_hi:[1,0]
	v_pk_mul_f32 v[48:49], v[48:49], v[82:83] op_sel_hi:[1,0]
	v_pk_mul_f32 v[46:47], v[46:47], v[82:83] op_sel_hi:[1,0]
	v_pk_mul_f32 v[44:45], v[44:45], v[82:83] op_sel_hi:[1,0]
	v_pk_mul_f32 v[42:43], v[42:43], v[82:83] op_sel_hi:[1,0]
	v_pk_mul_f32 v[40:41], v[40:41], v[82:83] op_sel_hi:[1,0]
	v_pk_mul_f32 v[38:39], v[38:39], v[82:83] op_sel_hi:[1,0]
	v_pk_mul_f32 v[36:37], v[36:37], v[82:83] op_sel_hi:[1,0]
	v_pk_mul_f32 v[34:35], v[34:35], v[82:83] op_sel_hi:[1,0]
	v_pk_mul_f32 v[32:33], v[32:33], v[82:83] op_sel_hi:[1,0]
	v_pk_mul_f32 v[30:31], v[30:31], v[82:83] op_sel_hi:[1,0]
	v_pk_mul_f32 v[28:29], v[28:29], v[82:83] op_sel_hi:[1,0]
	v_pk_mul_f32 v[26:27], v[26:27], v[82:83] op_sel_hi:[1,0]
	v_pk_mul_f32 v[24:25], v[24:25], v[82:83] op_sel_hi:[1,0]
	v_pk_mul_f32 v[22:23], v[22:23], v[82:83] op_sel_hi:[1,0]
	v_pk_mul_f32 v[20:21], v[20:21], v[82:83] op_sel_hi:[1,0]
	v_pk_mul_f32 v[18:19], v[18:19], v[82:83] op_sel_hi:[1,0]
	v_pk_mul_f32 v[16:17], v[16:17], v[82:83] op_sel_hi:[1,0]
	v_pk_mul_f32 v[14:15], v[14:15], v[82:83] op_sel_hi:[1,0]
	v_pk_mul_f32 v[12:13], v[12:13], v[82:83] op_sel_hi:[1,0]
	v_pk_mul_f32 v[10:11], v[10:11], v[82:83] op_sel_hi:[1,0]
	v_pk_mul_f32 v[8:9], v[8:9], v[82:83] op_sel_hi:[1,0]
	v_pk_mul_f32 v[6:7], v[6:7], v[82:83] op_sel_hi:[1,0]
	v_pk_mul_f32 v[4:5], v[4:5], v[82:83] op_sel_hi:[1,0]
	v_pk_mul_f32 v[2:3], v[2:3], v[82:83] op_sel_hi:[1,0]
	v_pk_mul_f32 v[0:1], v[0:1], v[82:83] op_sel_hi:[1,0]

.Lmla_dma_skip_t2:
	v_cvt_pk_bf16_f32 v124, v100, v101
	v_cvt_pk_bf16_f32 v125, v102, v103
	v_exp_f32_e32 v104, v104
	v_exp_f32_e32 v105, v105
	v_exp_f32_e32 v106, v106
	v_exp_f32_e32 v107, v107
	v_mfma_f32_32x32x16_bf16 v[80:95], v[176:179], v[168:171], v[80:95]
	ds_read_b128 v[252:255], v206 offset:20480
	v_exp_f32_e32 v108, v108
	v_exp_f32_e32 v109, v109
	v_exp_f32_e32 v110, v110
	v_exp_f32_e32 v111, v111
	s_add_i32 s4, s8, 4
	s_cmp_ge_u32 s4, s9
	s_waitcnt lgkmcnt(3)
	v_mfma_f32_32x32x16_bf16 v[80:95], v[180:183], v[172:175], v[80:95]
	ds_read_b128 v[176:179], v208 offset:20480
	v_mfma_f32_32x32x16_bf16 v[80:95], v[236:239], v[164:167], v[80:95]
	ds_read_b128 v[180:183], v210 offset:20480
	v_mfma_f32_32x32x16_bf16 v[80:95], v[240:243], v[160:163], v[80:95]
	ds_read_b128 v[236:239], v212 offset:20480
	s_waitcnt lgkmcnt(3)
	v_mfma_f32_32x32x16_bf16 v[80:95], v[244:247], v[152:155], v[80:95]
	ds_read_b128 v[240:243], v225 offset:32768
	v_mfma_f32_32x32x16_bf16 v[80:95], v[248:251], v[148:151], v[80:95]
	ds_read_b128 v[244:247], v225 offset:36864
	v_mfma_f32_32x32x16_bf16 v[80:95], v[252:255], v[140:143], v[80:95]
	ds_read_b128 v[248:251], v225 offset:40960
	s_waitcnt lgkmcnt(3)
	v_mfma_f32_32x32x16_bf16 v[80:95], v[176:179], v[136:139], v[80:95]
	ds_read_b128 v[252:255], v225 offset:45056
	v_mfma_f32_32x32x16_bf16 v[80:95], v[180:183], v[132:135], v[80:95]
	ds_read_b128 v[176:179], v226 offset:32768
	v_mfma_f32_32x32x16_bf16 v[80:95], v[236:239], v[128:131], v[80:95]
	ds_read_b128 v[180:183], v226 offset:36864
	s_waitcnt lgkmcnt(3)
	v_mfma_f32_32x32x16_bf16 v[48:63], v[240:243], v[122:125], v[48:63]
	ds_read_b128 v[236:239], v226 offset:40960
	s_nop 8
	v_max_f32_e32 v113, v81, v81
	v_max_f32_e32 v126, v80, v80
	v_max_f32_e32 v113, v126, v113
	v_max3_f32 v113, v113, v82, v83
	v_max3_f32 v113, v113, v84, v85
	v_max3_f32 v113, v113, v86, v87
	v_max3_f32 v113, v113, v88, v89
	v_mfma_f32_32x32x16_bf16 v[32:47], v[244:247], v[122:125], v[32:47]
	ds_read_b128 v[240:243], v226 offset:45056
	v_max3_f32 v113, v113, v90, v91
	v_max3_f32 v113, v113, v92, v93
	v_max3_f32 v113, v113, v94, v95
	v_mfma_f32_32x32x16_bf16 v[16:31], v[248:251], v[122:125], v[16:31]
	ds_read_b128 v[244:247], v214
	s_waitcnt lgkmcnt(3)
	v_mfma_f32_32x32x16_bf16 v[0:15], v[252:255], v[122:125], v[0:15]
	ds_read_b128 v[248:251], v215
	v_cvt_pk_bf16_f32 v118, v104, v105
	v_cvt_pk_bf16_f32 v119, v106, v107
	v_cvt_pk_bf16_f32 v120, v108, v109
	v_cvt_pk_bf16_f32 v121, v110, v111
	s_nop 0
	s_nop 0
	v_mfma_f32_32x32x16_bf16 v[48:63], v[176:179], v[118:121], v[48:63]
	ds_read_b128 v[252:255], v216
	v_mfma_f32_32x32x16_bf16 v[32:47], v[180:183], v[118:121], v[32:47]
	ds_read_b128 v[176:179], v217
	s_waitcnt lgkmcnt(3)
	v_mfma_f32_32x32x16_bf16 v[16:31], v[236:239], v[118:121], v[16:31]
	ds_read_b128 v[180:183], v218
	ds_bpermute_b32 v114, v229, v113
	v_mfma_f32_32x32x16_bf16 v[0:15], v[240:243], v[118:121], v[0:15]
	ds_read_b128 v[236:239], v219

.LBB0_873:
	v_exp_f32_e32 v113, v80
	v_exp_f32_e32 v126, v85
	v_exp_f32_e32 v127, v86
	v_mfma_f32_32x32x16_bf16 v[96:111], v[244:247], v[144:147], v[64:79]
	ds_read_b128 v[240:243], v220
	v_add_f32_e32 v231, 0, v113
	v_exp_f32_e32 v230, v87
	v_exp_f32_e32 v88, v88
	v_exp_f32_e32 v89, v89
	v_exp_f32_e32 v90, v90
	v_exp_f32_e32 v91, v91
	v_exp_f32_e32 v92, v92
	v_mfma_f32_32x32x16_bf16 v[96:111], v[248:251], v[156:159], v[96:111]
	ds_read_b128 v[244:247], v221
	v_exp_f32_e32 v93, v93
	s_add_u32 s62, s62, 0x180
	s_addc_u32 s61, s61, 0
	s_add_u32 s60, s60, 0x12000
	s_addc_u32 s59, s59, 0
	s_add_i32 s4, s16, 3
	v_mfma_f32_32x32x16_bf16 v[96:111], v[252:255], v[168:171], v[96:111]
	ds_read_b128 v[248:251], v206
	s_cmp_le_u32 s4, s9
	v_mfma_f32_32x32x16_bf16 v[96:111], v[176:179], v[172:175], v[96:111]
	ds_read_b128 v[252:255], v208
	v_mfma_f32_32x32x16_bf16 v[96:111], v[180:183], v[164:167], v[96:111]
	ds_read_b128 v[176:179], v210
	s_waitcnt lgkmcnt(3)
	v_mfma_f32_32x32x16_bf16 v[96:111], v[236:239], v[160:163], v[96:111]
	ds_read_b128 v[180:183], v212
	v_mfma_f32_32x32x16_bf16 v[96:111], v[240:243], v[152:155], v[96:111]
	ds_read_b128 v[236:239], v227 offset:32768
	v_mfma_f32_32x32x16_bf16 v[96:111], v[244:247], v[148:151], v[96:111]
	ds_read_b128 v[240:243], v227 offset:36864
	s_waitcnt lgkmcnt(3)
	v_mfma_f32_32x32x16_bf16 v[96:111], v[248:251], v[140:143], v[96:111]
	ds_read_b128 v[244:247], v227 offset:40960
	v_mfma_f32_32x32x16_bf16 v[96:111], v[252:255], v[136:139], v[96:111]
	ds_read_b128 v[248:251], v227 offset:45056
	v_exp_f32_e32 v118, v81
	v_exp_f32_e32 v119, v82
	v_exp_f32_e32 v120, v83
	v_exp_f32_e32 v121, v84
	v_mfma_f32_32x32x16_bf16 v[96:111], v[176:179], v[132:135], v[96:111]
	ds_read_b128 v[252:255], v228 offset:36864
	v_cvt_pk_bf16_f32 v114, v113, v118
	v_add_f32_e32 v113, v118, v231
	v_add_f32_e32 v113, v119, v113
	v_add_f32_e32 v113, v120, v113
	v_add_f32_e32 v113, v121, v113
	v_cvt_pk_bf16_f32 v115, v119, v120
	v_cvt_pk_bf16_f32 v116, v121, v126
	v_cvt_pk_bf16_f32 v117, v127, v230
	v_add_f32_e32 v113, v126, v113
	s_waitcnt lgkmcnt(3)
	v_mfma_f32_32x32x16_bf16 v[96:111], v[180:183], v[128:131], v[96:111]
	ds_read_b128 v[176:179], v228 offset:32768
	v_exp_f32_e32 v118, v94
	v_exp_f32_e32 v119, v95
	v_mfma_f32_32x32x16_bf16 v[48:63], v[236:239], v[114:117], v[48:63]
	ds_read_b128 v[180:183], v228 offset:40960
	v_add_f32_e32 v80, v127, v113
	v_add_f32_e32 v80, v230, v80
	v_add_f32_e32 v113, v88, v80
	v_cvt_pk_bf16_f32 v88, v88, v89
	v_mfma_f32_32x32x16_bf16 v[32:47], v[240:243], v[114:117], v[32:47]
	ds_read_b128 v[236:239], v228 offset:45056
	v_add_f32_e32 v84, v89, v113
	v_add_f32_e32 v84, v90, v84
	v_add_f32_e32 v84, v91, v84
	v_add_f32_e32 v113, v92, v84
	v_add_f32_e32 v113, v93, v113
	v_cvt_pk_bf16_f32 v89, v90, v91
	s_waitcnt lgkmcnt(3)
	v_mfma_f32_32x32x16_bf16 v[16:31], v[244:247], v[114:117], v[16:31]
	v_cvt_pk_bf16_f32 v90, v92, v93
	v_cvt_pk_bf16_f32 v91, v118, v119
	v_mfma_f32_32x32x16_bf16 v[0:15], v[248:251], v[114:117], v[0:15]
	v_max_f32_e32 v114, v97, v97
	v_max_f32_e32 v115, v96, v96
	v_max_f32_e32 v114, v115, v114
	v_max3_f32 v114, v114, v98, v99
	v_mfma_f32_32x32x16_bf16 v[32:47], v[252:255], v[88:91], v[32:47]
	s_waitcnt vmcnt(0)
	s_barrier
	s_waitcnt lgkmcnt(2)
	v_mfma_f32_32x32x16_bf16 v[48:63], v[176:179], v[88:91], v[48:63]
	v_max3_f32 v80, v114, v100, v101
	v_max3_f32 v80, v80, v102, v103
	v_max3_f32 v80, v80, v104, v105
	v_max3_f32 v80, v80, v106, v107
	v_max3_f32 v80, v80, v108, v109
	v_max3_f32 v80, v80, v110, v111
	ds_bpermute_b32 v81, v229, v80
	s_waitcnt lgkmcnt(2)
	v_mfma_f32_32x32x16_bf16 v[16:31], v[180:183], v[88:91], v[16:31]
	v_add_f32_e32 v82, v118, v113
	v_add_f32_e32 v82, v119, v82
	v_add_f32_e32 v230, v112, v82
	s_waitcnt lgkmcnt(0)
	v_max_f32_e32 v81, v81, v81
	v_max_f32_e32 v82, v80, v81
	v_mfma_f32_32x32x16_bf16 v[0:15], v[236:239], v[88:91], v[0:15]
	s_cbranch_scc0 .LBB0_875
	s_mov_b32 s8, s16
	v_cmp_lt_f32_e32 vcc, 0, v82
	s_cbranch_vccnz .LBB0_858
	s_branch .LBB0_859
